# ret_scan: the never-taken denormal-scaling guard around the 8 per-step rsq (argument is q/128 + 1e-6 >= 1e-6) removed, 5 instructions per rsq; results unchanged
# baseline (speedup 1.0000x reference)
.LBB0_190:
	v_lshl_add_u32 v81, v83, 2, v147
	s_waitcnt lgkmcnt(0)
	s_barrier
	ds_read_b128 v[170:173], v81
	ds_read_b128 v[174:177], v81 offset:256
	ds_read_b128 v[178:181], v81 offset:512
	ds_read_b128 v[182:185], v81 offset:768
	ds_read_b128 v[186:189], v81 offset:1024
	ds_read_b128 v[190:193], v81 offset:1280
	ds_read_b128 v[194:197], v81 offset:1536
	ds_read_b128 v[198:201], v81 offset:1792
	ds_read_b128 v[212:215], v81 offset:64
	ds_read_b128 v[216:219], v81 offset:320
	ds_read_b128 v[220:223], v81 offset:576
	ds_read_b128 v[224:227], v81 offset:832
	ds_read_b128 v[228:231], v81 offset:1088
	ds_read_b128 v[232:235], v81 offset:1344
	ds_read_b128 v[236:239], v81 offset:1600
	ds_read_b128 v[240:243], v81 offset:1856
	s_mov_b32 s4, 0xa180000
	v_lshl_add_u64 v[88:89], v[88:89], 0, s[82:83]
	v_lshl_add_u64 v[86:87], v[86:87], 0, s[82:83]
	v_lshl_add_u64 v[90:91], v[90:91], 0, s[82:83]
	s_waitcnt lgkmcnt(14)
	v_pk_add_f32 v[72:73], v[172:173], v[176:177]
	s_waitcnt lgkmcnt(14)
	v_pk_add_f32 v[70:71], v[170:171], v[174:175]
	v_lshl_add_u64 v[92:93], v[92:93], 0, s[74:75]
	s_mov_b32 s22, s23
	s_waitcnt lgkmcnt(13)
	v_pk_add_f32 v[72:73], v[72:73], v[180:181]
	s_waitcnt lgkmcnt(13)
	v_pk_add_f32 v[70:71], v[70:71], v[178:179]
	s_waitcnt lgkmcnt(12)
	v_pk_add_f32 v[72:73], v[72:73], v[184:185]
	s_waitcnt lgkmcnt(12)
	v_pk_add_f32 v[70:71], v[70:71], v[182:183]
	s_waitcnt lgkmcnt(11)
	v_pk_add_f32 v[72:73], v[72:73], v[188:189]
	s_waitcnt lgkmcnt(11)
	v_pk_add_f32 v[70:71], v[70:71], v[186:187]
	s_waitcnt lgkmcnt(10)
	v_pk_add_f32 v[72:73], v[72:73], v[192:193]
	s_waitcnt lgkmcnt(10)
	v_pk_add_f32 v[70:71], v[70:71], v[190:191]
	s_waitcnt lgkmcnt(9)
	v_pk_add_f32 v[72:73], v[72:73], v[196:197]
	s_waitcnt lgkmcnt(9)
	v_pk_add_f32 v[70:71], v[70:71], v[194:195]
	s_waitcnt lgkmcnt(8)
	v_pk_add_f32 v[66:67], v[70:71], v[198:199]
	s_nop 0
	v_fmamk_f32 v66, v66, 0x3c000000, v169
	s_waitcnt lgkmcnt(8)
	v_pk_add_f32 v[68:69], v[72:73], v[200:201]
	v_rsq_f32_e32 v66, v66
	s_nop 0
	v_mul_f32_e32 v62, v62, v66
	v_lshlrev_b32_e32 v66, 2, v121
	v_mul_lo_u32 v70, v120, s62
	v_add3_u32 v70, v115, v66, v70
	v_fmamk_f32 v66, v67, 0x3c000000, v169
	s_nop 0
	v_rsq_f32_e32 v66, v66
	s_nop 0
	v_mul_f32_e32 v63, v63, v66
	v_add_u32_e32 v66, 0x4200, v70
	ds_write2_b32 v66, v62, v63 offset1:132
	v_fmamk_f32 v62, v68, 0x3c000000, v169
	s_nop 0
	v_rsq_f32_e32 v62, v62
	s_nop 0
	v_fmamk_f32 v63, v69, 0x3c000000, v169
	v_mul_f32_e32 v62, v64, v62
	s_nop 0
	v_rsq_f32_e32 v63, v63
	s_nop 0
	v_mul_f32_e32 v63, v65, v63
	v_add_u32_e32 v64, 0x4600, v70
	ds_write2_b32 v64, v62, v63 offset0:8 offset1:140
	s_waitcnt lgkmcnt(8)
	v_pk_add_f32 v[68:69], v[214:215], v[218:219]
	s_waitcnt lgkmcnt(8)
	v_pk_add_f32 v[66:67], v[212:213], v[216:217]
	s_waitcnt lgkmcnt(7)
	v_pk_add_f32 v[68:69], v[68:69], v[222:223]
	s_waitcnt lgkmcnt(7)
	v_pk_add_f32 v[66:67], v[66:67], v[220:221]
	s_waitcnt lgkmcnt(6)
	v_pk_add_f32 v[68:69], v[68:69], v[226:227]
	s_waitcnt lgkmcnt(6)
	v_pk_add_f32 v[66:67], v[66:67], v[224:225]
	s_waitcnt lgkmcnt(5)
	v_pk_add_f32 v[68:69], v[68:69], v[230:231]
	s_waitcnt lgkmcnt(5)
	v_pk_add_f32 v[66:67], v[66:67], v[228:229]
	s_waitcnt lgkmcnt(4)
	v_pk_add_f32 v[68:69], v[68:69], v[234:235]
	s_waitcnt lgkmcnt(4)
	v_pk_add_f32 v[66:67], v[66:67], v[232:233]
	s_waitcnt lgkmcnt(3)
	v_pk_add_f32 v[68:69], v[68:69], v[238:239]
	s_waitcnt lgkmcnt(3)
	v_pk_add_f32 v[66:67], v[66:67], v[236:237]
	s_waitcnt lgkmcnt(2)
	v_pk_add_f32 v[62:63], v[66:67], v[240:241]
	s_nop 0
	v_fmamk_f32 v62, v62, 0x3c000000, v169
	s_waitcnt lgkmcnt(2)
	v_pk_add_f32 v[64:65], v[68:69], v[242:243]
	v_rsq_f32_e32 v62, v62
	s_cmp_lt_u32 s22, 30
	s_cbranch_scc0 .Lrv_c2_n0
	s_waitcnt vmcnt(4)
	s_branch .Lrv_c2_end

.Lrv_c2_end:
	v_and_b32_e32 v67, 0xffff0000, v46
	v_mul_f32_e32 v58, v58, v62
	v_fmamk_f32 v62, v63, 0x3c000000, v169
	v_lshlrev_b32_e32 v66, 16, v46
	v_rsq_f32_e32 v62, v62
	s_nop 0
	v_mul_f32_e32 v59, v59, v62
	v_add_u32_e32 v62, 0x6200, v70
	ds_write2_b32 v62, v58, v59 offset0:64 offset1:196
	v_fmamk_f32 v58, v64, 0x3c000000, v169
	s_nop 0
	v_rsq_f32_e32 v58, v58
	s_nop 0
	v_fmamk_f32 v59, v65, 0x3c000000, v169
	v_mul_f32_e32 v58, v60, v58
	s_nop 0
	v_rsq_f32_e32 v59, v59
	s_nop 0
	v_mul_f32_e32 v59, v61, v59
	v_add_u32_e32 v60, 0x6600, v70
	ds_write2_b32 v60, v58, v59 offset0:72 offset1:204
	ds_read_b128 v[58:61], v113
	ds_read_b128 v[62:65], v113 offset:16
	s_waitcnt lgkmcnt(1)
	v_pk_mul_f32 v[58:59], v[58:59], v[66:67]
	s_nop 0
	v_cvt_pk_bf16_f32 v46, v58, v59
	v_lshlrev_b32_e32 v58, 16, v47
	v_and_b32_e32 v59, 0xffff0000, v47
	v_pk_mul_f32 v[58:59], v[60:61], v[58:59]
	s_nop 0
	v_cvt_pk_bf16_f32 v47, v58, v59
	v_lshlrev_b32_e32 v58, 16, v48
	v_and_b32_e32 v59, 0xffff0000, v48
	s_waitcnt lgkmcnt(0)
	v_pk_mul_f32 v[58:59], v[62:63], v[58:59]
	s_nop 0
	v_cvt_pk_bf16_f32 v48, v58, v59
	v_lshlrev_b32_e32 v58, 16, v49
	v_and_b32_e32 v59, 0xffff0000, v49
	v_pk_mul_f32 v[58:59], v[64:65], v[58:59]
	s_nop 0
	v_cvt_pk_bf16_f32 v49, v58, v59
	v_add_co_u32_e32 v58, vcc, s4, v96
	s_nop 1
	v_addc_co_u32_e32 v59, vcc, 0, v97, vcc
	s_andn2_b64 vcc, exec, s[48:49]
	global_store_dwordx4 v[58:59], v[46:49], off
	s_cbranch_vccz .LBB0_271

.LBB0_217:
	v_lshl_add_u32 v81, v83, 2, v143
	s_waitcnt lgkmcnt(0)
	s_barrier
	ds_read_b128 v[170:173], v81
	ds_read_b128 v[174:177], v81 offset:256
	ds_read_b128 v[178:181], v81 offset:512
	ds_read_b128 v[182:185], v81 offset:768
	ds_read_b128 v[186:189], v81 offset:1024
	ds_read_b128 v[190:193], v81 offset:1280
	ds_read_b128 v[194:197], v81 offset:1536
	ds_read_b128 v[198:201], v81 offset:1792
	ds_read_b128 v[212:215], v81 offset:64
	ds_read_b128 v[216:219], v81 offset:320
	ds_read_b128 v[220:223], v81 offset:576
	ds_read_b128 v[224:227], v81 offset:832
	ds_read_b128 v[228:231], v81 offset:1088
	ds_read_b128 v[232:235], v81 offset:1344
	ds_read_b128 v[236:239], v81 offset:1600
	ds_read_b128 v[240:243], v81 offset:1856
	s_waitcnt lgkmcnt(14)
	v_pk_add_f32 v[72:73], v[172:173], v[176:177]
	s_waitcnt lgkmcnt(14)
	v_pk_add_f32 v[70:71], v[170:171], v[174:175]
	s_waitcnt lgkmcnt(13)
	v_pk_add_f32 v[72:73], v[72:73], v[180:181]
	s_waitcnt lgkmcnt(13)
	v_pk_add_f32 v[70:71], v[70:71], v[178:179]
	s_waitcnt lgkmcnt(12)
	v_pk_add_f32 v[72:73], v[72:73], v[184:185]
	s_waitcnt lgkmcnt(12)
	v_pk_add_f32 v[70:71], v[70:71], v[182:183]
	s_waitcnt lgkmcnt(11)
	v_pk_add_f32 v[72:73], v[72:73], v[188:189]
	s_waitcnt lgkmcnt(11)
	v_pk_add_f32 v[70:71], v[70:71], v[186:187]
	s_waitcnt lgkmcnt(10)
	v_pk_add_f32 v[72:73], v[72:73], v[192:193]
	s_waitcnt lgkmcnt(10)
	v_pk_add_f32 v[70:71], v[70:71], v[190:191]
	s_waitcnt lgkmcnt(9)
	v_pk_add_f32 v[72:73], v[72:73], v[196:197]
	s_waitcnt lgkmcnt(9)
	v_pk_add_f32 v[70:71], v[70:71], v[194:195]
	s_waitcnt lgkmcnt(8)
	v_pk_add_f32 v[66:67], v[70:71], v[198:199]
	s_nop 0
	v_fmamk_f32 v66, v66, 0x3c000000, v169
	s_waitcnt lgkmcnt(8)
	v_pk_add_f32 v[68:69], v[72:73], v[200:201]
	v_rsq_f32_e32 v66, v66
	s_nop 0
	v_mul_f32_e32 v62, v62, v66
	v_lshlrev_b32_e32 v66, 2, v97
	v_mul_lo_u32 v70, v96, s62
	v_add3_u32 v70, v115, v66, v70
	v_fmamk_f32 v66, v67, 0x3c000000, v169
	v_lshl_add_u64 v[96:97], s[96:97], 0, v[92:93]
	v_rsq_f32_e32 v66, v66
	s_nop 0
	v_mul_f32_e32 v63, v63, v66
	ds_write2_b32 v70, v62, v63 offset1:132
	v_fmamk_f32 v62, v68, 0x3c000000, v169
	s_nop 0
	v_rsq_f32_e32 v62, v62
	s_nop 0
	v_fmamk_f32 v63, v69, 0x3c000000, v169
	v_mul_f32_e32 v62, v64, v62
	s_nop 0
	v_rsq_f32_e32 v63, v63
	s_nop 0
	v_mul_f32_e32 v63, v65, v63
	v_add_u32_e32 v64, 0x400, v70
	ds_write2_b32 v64, v62, v63 offset0:8 offset1:140
	s_waitcnt lgkmcnt(8)
	v_pk_add_f32 v[68:69], v[214:215], v[218:219]
	s_waitcnt lgkmcnt(8)
	v_pk_add_f32 v[66:67], v[212:213], v[216:217]
	s_waitcnt lgkmcnt(7)
	v_pk_add_f32 v[68:69], v[68:69], v[222:223]
	s_waitcnt lgkmcnt(7)
	v_pk_add_f32 v[66:67], v[66:67], v[220:221]
	s_waitcnt lgkmcnt(6)
	v_pk_add_f32 v[68:69], v[68:69], v[226:227]
	s_waitcnt lgkmcnt(6)
	v_pk_add_f32 v[66:67], v[66:67], v[224:225]
	s_waitcnt lgkmcnt(5)
	v_pk_add_f32 v[68:69], v[68:69], v[230:231]
	s_waitcnt lgkmcnt(5)
	v_pk_add_f32 v[66:67], v[66:67], v[228:229]
	s_waitcnt lgkmcnt(4)
	v_pk_add_f32 v[68:69], v[68:69], v[234:235]
	s_waitcnt lgkmcnt(4)
	v_pk_add_f32 v[66:67], v[66:67], v[232:233]
	s_waitcnt lgkmcnt(3)
	v_pk_add_f32 v[68:69], v[68:69], v[238:239]
	s_waitcnt lgkmcnt(3)
	v_pk_add_f32 v[66:67], v[66:67], v[236:237]
	s_waitcnt lgkmcnt(2)
	v_pk_add_f32 v[62:63], v[66:67], v[240:241]
	s_nop 0
	v_fmamk_f32 v62, v62, 0x3c000000, v169
	s_waitcnt lgkmcnt(2)
	v_pk_add_f32 v[64:65], v[68:69], v[242:243]
	v_rsq_f32_e32 v62, v62
	s_nop 0
	v_mul_f32_e32 v58, v58, v62
	v_fmamk_f32 v62, v63, 0x3c000000, v169
	s_nop 0
	v_rsq_f32_e32 v62, v62
	s_nop 0
	v_mul_f32_e32 v59, v59, v62
	v_add_u32_e32 v62, 0x2000, v70
	ds_write2_b32 v62, v58, v59 offset0:64 offset1:196
	v_fmamk_f32 v58, v64, 0x3c000000, v169
	s_nop 0
	v_rsq_f32_e32 v58, v58
	s_nop 0
	v_fmamk_f32 v59, v65, 0x3c000000, v169
	v_mul_f32_e32 v58, v60, v58
	s_nop 0
	v_rsq_f32_e32 v59, v59
	s_nop 0
	v_mul_f32_e32 v59, v61, v59
	v_add_u32_e32 v60, 0x2400, v70
	s_andn2_b64 vcc, exec, s[52:53]
	ds_write2_b32 v60, v58, v59 offset0:72 offset1:204
	s_cbranch_vccnz .LBB0_219
	ds_read_b128 v[58:61], v109
	ds_read_b128 v[62:65], v109 offset:16
	s_cmp_lt_u32 s22, 29
	s_cbranch_scc0 .Lrv_c1_n0
	s_waitcnt vmcnt(4)
	s_branch .Lrv_c1_end
